# speedup vs baseline: 1.0046x; 1.0004x over previous
; __device__ __forceinline__ f32x4 mfma16(bf16x8 a, bf16x8 b, f32x4 c) { return __builtin_amdgcn_mfma_f32_16x16x32_bf16(a, b, c, 0, 0, 0); }
; __device__ __forceinline__ void attn_tile(const bf16_t* Kl, const bf16_t* VTl, const float* tab, const bf16x8 (&qf)[4], f32x4 (&o)[8], float& m, float& l, int qp, int kp0, int kvalid, int li, int fq) {
;     ...
;     for (int kb = 0; kb < 4; ++kb) { s[kb] = (f32x4){0.f, 0.f, 0.f, 0.f};
; #pragma unroll
;         for (int ks = 0; ks < 4; ++ks) { const bf16x8 a = *(const bf16x8*)(Kl + (16 * kb + li) * 136 + 32 * ks + 8 * fq); s[kb] = mfma16(a, qf[ks], s[kb]); } }
;     float mx = -1e30f;
; #pragma unroll
;     for (int kb = 0; kb < 4; ++kb)
; #pragma unroll
;         for (int r = 0; r < 4; ++r) { const int kp = kp0 + 16 * kb + 4 * fq + r; int rel = qp - kp; rel = min(max(rel, -128), 128) + 128;
;             float v = s[kb][r] + tab[rel]; v = (kp < kvalid) ? v : -1e30f; s[kb][r] = v; mx = fmaxf(mx, v); }
;     ...
;         for (int db = 0; db < 8; ++db) { const u32x2 lo = *(const u32x2*)(VTl + (16 * db + li) * 72 + 32 * k2 + 4 * fq); const u32x2 hi = *(const u32x2*)(VTl + (16 * db + li) * 72 + 32 * k2 + 16 + 4 * fq);
.LBB0_819:
	s_cmp_lt_i32 s4, s5
	s_cselect_b64 s[8:9], -1, 0
	s_cmp_gt_i32 s4, s3
	s_cselect_b64 s[10:11], -1, 0
	s_or_b64 s[8:9], s[8:9], s[10:11]
	s_and_b64 vcc, exec, s[8:9]
	s_waitcnt lgkmcnt(0)
	s_barrier
	s_cbranch_vccnz .LBB0_816
	v_add3_u32 v99, s6, v76, v93
	ds_read_b128 v[142:145], v99 offset:1280
	ds_read_b128 v[146:149], v99 offset:1344
	ds_read_b128 v[150:153], v99 offset:1408
	ds_read_b128 v[154:157], v99 offset:1472
	ds_read_b128 v[158:161], v99 offset:5632
	ds_read_b128 v[162:165], v99 offset:5696
	ds_read_b128 v[166:169], v99 offset:5760
	ds_read_b128 v[170:173], v99 offset:5824
	ds_read_b128 v[174:177], v99 offset:9984
	ds_read_b128 v[178:181], v99 offset:10048
	ds_read_b128 v[182:185], v99 offset:10112
	ds_read_b128 v[186:189], v99 offset:10176
	s_waitcnt lgkmcnt(11)
	v_mfma_f32_16x16x32_bf16 v[64:67], v[142:145], v[0:3], 0
	s_waitcnt lgkmcnt(10)
	v_mfma_f32_16x16x32_bf16 v[64:67], v[146:149], v[4:7], v[64:67]
	s_waitcnt lgkmcnt(9)
	v_mfma_f32_16x16x32_bf16 v[64:67], v[150:153], v[8:11], v[64:67]
	s_waitcnt lgkmcnt(8)
	v_mfma_f32_16x16x32_bf16 v[100:103], v[154:157], v[12:15], v[64:67]
	s_nop 4
	ds_read_b128 v[190:193], v99 offset:14336
	ds_read_b128 v[194:197], v99 offset:14400
	ds_read_b128 v[198:201], v99 offset:14464
	ds_read_b128 v[202:205], v99 offset:14528
	v_add_u32_e32 v99, 51, v95
	v_med3_i32 v99, v99, s74, v113
	s_waitcnt lgkmcnt(11)
	v_mfma_f32_16x16x32_bf16 v[64:67], v[158:161], v[0:3], 0
	s_waitcnt lgkmcnt(10)
	v_mfma_f32_16x16x32_bf16 v[64:67], v[162:165], v[4:7], v[64:67]
	s_waitcnt lgkmcnt(9)
	v_mfma_f32_16x16x32_bf16 v[64:67], v[166:169], v[8:11], v[64:67]
	s_waitcnt lgkmcnt(8)
	v_mfma_f32_16x16x32_bf16 v[72:75], v[170:173], v[12:15], v[64:67]
	s_nop 4
	s_waitcnt lgkmcnt(7)
	v_mfma_f32_16x16x32_bf16 v[64:67], v[174:177], v[0:3], 0
	s_waitcnt lgkmcnt(6)
	v_mfma_f32_16x16x32_bf16 v[64:67], v[178:181], v[4:7], v[64:67]
	s_waitcnt lgkmcnt(5)
	v_mfma_f32_16x16x32_bf16 v[64:67], v[182:185], v[8:11], v[64:67]
	s_waitcnt lgkmcnt(4)
	v_mfma_f32_16x16x32_bf16 v[68:71], v[186:189], v[12:15], v[64:67]
	s_nop 4
	s_waitcnt lgkmcnt(3)
	v_mfma_f32_16x16x32_bf16 v[64:67], v[190:193], v[0:3], 0
	s_waitcnt lgkmcnt(2)
	v_mfma_f32_16x16x32_bf16 v[64:67], v[194:197], v[4:7], v[64:67]
	s_waitcnt lgkmcnt(1)
	v_mfma_f32_16x16x32_bf16 v[64:67], v[198:201], v[8:11], v[64:67]
	s_waitcnt lgkmcnt(0)
	v_mfma_f32_16x16x32_bf16 v[64:67], v[202:205], v[12:15], v[64:67]
	v_lshlrev_b32_e32 v206, 1, v81
	v_add3_u32 v206, s6, v96, v206
	v_add_u32_e32 v207, 0x5000, v206
	v_add_u32_e32 v208, 0x5800, v206
	v_add_u32_e32 v209, 0x6000, v206
	v_add_u32_e32 v210, 0x6800, v206
	v_add_u32_e32 v211, 0x7000, v206
	v_add_u32_e32 v212, 0x7800, v206
	v_add_u32_e32 v213, 0x8800, v206
	v_add_u32_e32 v206, 0x4800, v206
	ds_read2_b64 v[142:145], v206 offset0:32 offset1:36
	ds_read2_b64 v[146:149], v207 offset0:64 offset1:68
	ds_read2_b64 v[150:153], v208 offset0:96 offset1:100
	ds_read2_b64 v[154:157], v209 offset0:128 offset1:132
	ds_read2_b64 v[158:161], v210 offset0:160 offset1:164
	ds_read2_b64 v[162:165], v211 offset0:192 offset1:196
	ds_read2_b64 v[166:169], v212 offset0:224 offset1:228
	ds_read2_b64 v[170:173], v213 offset1:4
	ds_read2_b64 v[174:177], v206 offset0:40 offset1:44
	ds_read2_b64 v[178:181], v207 offset0:72 offset1:76
	ds_read2_b64 v[182:185], v208 offset0:104 offset1:108
	ds_read2_b64 v[186:189], v209 offset0:136 offset1:140
	s_waitcnt lgkmcnt(8)
	ds_read2_b64 v[190:193], v210 offset0:168 offset1:172
	ds_read2_b64 v[194:197], v211 offset0:200 offset1:204
	ds_read2_b64 v[198:201], v212 offset0:232 offset1:236
	ds_read2_b64 v[202:205], v213 offset0:8 offset1:12
	v_add_u32_e32 v104, 49, v95
	v_med3_i32 v104, v104, s74, v113
	v_lshl_add_u32 v99, v99, 2, 0
	v_lshl_add_u32 v104, v104, 2, 0
	ds_read_b32 v99, v99 offset:512
	ds_read_b32 v104, v104 offset:512
	s_waitcnt lgkmcnt(0)
	v_add_f32_e32 v102, v102, v104
	v_add_u32_e32 v104, 48, v95
	v_med3_i32 v104, v104, s74, v113
	v_lshl_add_u32 v104, v104, 2, 0
	ds_read_b32 v104, v104 offset:512
	s_waitcnt lgkmcnt(0)
	v_add_f32_e32 v103, v103, v104
	v_add_u32_e32 v104, 35, v95
	v_med3_i32 v104, v104, s74, v113
	v_lshl_add_u32 v104, v104, 2, 0
	ds_read_b32 v104, v104 offset:512
	s_waitcnt lgkmcnt(0)
	v_add_f32_e32 v104, v72, v104
	v_add_u32_e32 v72, 34, v95
	v_med3_i32 v72, v72, s74, v113
	v_lshl_add_u32 v72, v72, 2, 0
	ds_read_b32 v72, v72 offset:512
	v_add_f32_e32 v99, v100, v99
	v_add_u32_e32 v100, 50, v95
	v_med3_i32 v100, v100, s74, v113
	v_lshl_add_u32 v100, v100, 2, 0
	ds_read_b32 v100, v100 offset:512
	s_waitcnt lgkmcnt(1)
	v_add_f32_e32 v73, v73, v72
	s_waitcnt lgkmcnt(0)
	v_add_f32_e32 v100, v101, v100
	v_max3_f32 v101, v99, s97, v100
	v_max3_f32 v101, v101, v102, v103
	v_max3_f32 v72, v101, v104, v73
	v_add_u32_e32 v101, 33, v95
	v_med3_i32 v101, v101, s74, v113
	v_lshl_add_u32 v101, v101, 2, 0
	ds_read_b32 v101, v101 offset:512
	s_waitcnt lgkmcnt(0)
	v_add_f32_e32 v74, v74, v101
	v_add_u32_e32 v101, 32, v95
	v_med3_i32 v101, v101, s74, v113
	v_lshl_add_u32 v101, v101, 2, 0
	ds_read_b32 v101, v101 offset:512
	s_waitcnt lgkmcnt(0)
	v_add_f32_e32 v75, v75, v101
	v_add_u32_e32 v101, 19, v95
	v_med3_i32 v101, v101, s74, v113
	v_lshl_add_u32 v101, v101, 2, 0
	ds_read_b32 v101, v101 offset:512
	v_max3_f32 v72, v72, v74, v75
	s_waitcnt lgkmcnt(0)
	v_add_f32_e32 v101, v68, v101
	v_add_u32_e32 v68, 18, v95
	v_med3_i32 v68, v68, s74, v113
	v_lshl_add_u32 v68, v68, 2, 0
	ds_read_b32 v68, v68 offset:512
	s_waitcnt lgkmcnt(0)
	v_add_f32_e32 v105, v69, v68
	v_add_u32_e32 v69, 17, v95
	v_med3_i32 v69, v69, s74, v113
	v_lshl_add_u32 v69, v69, 2, 0
	ds_read_b32 v69, v69 offset:512
	v_max3_f32 v68, v72, v101, v105
	s_waitcnt lgkmcnt(0)
; __device__ __forceinline__ unsigned cvt_pk(float lo, float hi) { unsigned r; asm("v_cvt_pk_bf16_f32 %0, %1, %2" : "=v"(r) : "v"(lo), "v"(hi)); return r; }
; __device__ __forceinline__ f32x4 mfma16(bf16x8 a, bf16x8 b, f32x4 c) { return __builtin_amdgcn_mfma_f32_16x16x32_bf16(a, b, c, 0, 0, 0); }
; __device__ __forceinline__ void attn_tile(const bf16_t* Kl, const bf16_t* VTl, const float* tab, const bf16x8 (&qf)[4], f32x4 (&o)[8], float& m, float& l, int qp, int kp0, int kvalid, int li, int fq) {
;     ...
;         for (int r = 0; r < 4; ++r) { const int kp = kp0 + 16 * kb + 4 * fq + r; int rel = qp - kp; rel = min(max(rel, -128), 128) + 128;
;             float v = s[kb][r] + tab[rel]; v = (kp < kvalid) ? v : -1e30f; s[kb][r] = v; mx = fmaxf(mx, v); }
;     mx = fmaxf(mx, __shfl_xor(mx, 16)); mx = fmaxf(mx, __shfl_xor(mx, 32));
;     const float mn = fmaxf(m, mx), alpha = __expf(m - mn); m = mn;
;     float ps = 0.f; unsigned pk[4][2];
; #pragma unroll
;     for (int kb = 0; kb < 4; ++kb) { float e[4];
; #pragma unroll
;         for (int r = 0; r < 4; ++r) { e[r] = __expf(s[kb][r] - mn); ps += e[r]; }
;         pk[kb][0] = cvt_pk(e[0], e[1]); pk[kb][1] = cvt_pk(e[2], e[3]); }
;     l = l * alpha + ps;
; #pragma unroll
;     for (int db = 0; db < 8; ++db) o[db] = o[db] * alpha;
; #pragma unroll
;     for (int k2 = 0; k2 < 2; ++k2) { const bf16x8 pb = mk8(pk[2 * k2][0], pk[2 * k2][1], pk[2 * k2 + 1][0], pk[2 * k2 + 1][1]);
; #pragma unroll
;         for (int db = 0; db < 8; ++db) { const u32x2 lo = *(const u32x2*)(VTl + (16 * db + li) * 72 + 32 * k2 + 4 * fq); const u32x2 hi = *(const u32x2*)(VTl + (16 * db + li) * 72 + 32 * k2 + 16 + 4 * fq);
;             o[db] = mfma16(mk8(lo.x, lo.y, hi.x, hi.y), pb, o[db]); } }
	v_add_f32_e32 v106, v70, v69
	v_add_u32_e32 v69, 16, v95
	v_med3_i32 v69, v69, s74, v113
	v_lshl_add_u32 v69, v69, 2, 0
	ds_read_b32 v69, v69 offset:512
	s_waitcnt lgkmcnt(0)
	v_add_f32_e32 v107, v71, v69
	v_add_u32_e32 v69, 3, v95
	v_med3_i32 v69, v69, s74, v113
	v_lshl_add_u32 v69, v69, 2, 0
	ds_read_b32 v69, v69 offset:512
	v_max3_f32 v68, v68, v106, v107
	s_waitcnt lgkmcnt(0)
	v_add_f32_e32 v108, v64, v69
	v_add_u32_e32 v64, 2, v95
	v_med3_i32 v64, v64, s74, v113
	v_lshl_add_u32 v64, v64, 2, 0
	ds_read_b32 v64, v64 offset:512
	s_waitcnt lgkmcnt(0)
	v_add_f32_e32 v109, v65, v64
	v_add_u32_e32 v65, 1, v95
	v_med3_i32 v65, v65, s74, v113
	v_lshl_add_u32 v65, v65, 2, 0
	ds_read_b32 v65, v65 offset:512
	v_max3_f32 v64, v68, v108, v109
	v_and_b32_e32 v68, 64, v112
	v_add_u32_e32 v68, 64, v68
	s_waitcnt lgkmcnt(0)
	v_add_f32_e32 v66, v66, v65
	v_med3_i32 v65, v95, s74, v113
	v_lshl_add_u32 v65, v65, 2, 0
	ds_read_b32 v65, v65 offset:512
	s_waitcnt lgkmcnt(0)
	v_add_f32_e32 v67, v67, v65
	v_xor_b32_e32 v65, 16, v112
	v_cmp_lt_i32_e32 vcc, v65, v68
	v_max3_f32 v64, v64, v66, v67
	s_nop 0
	v_cndmask_b32_e32 v65, v112, v65, vcc
	v_lshlrev_b32_e32 v65, 2, v65
	ds_bpermute_b32 v65, v65, v64
	s_waitcnt lgkmcnt(0)
	v_max_f32_e32 v65, v65, v65
	v_max_f32_e32 v64, v64, v65
	v_xor_b32_e32 v65, 32, v112
	v_cmp_lt_i32_e32 vcc, v65, v68
	s_nop 1
	v_cndmask_b32_e32 v65, v112, v65, vcc
	v_lshlrev_b32_e32 v65, 2, v65
	ds_bpermute_b32 v65, v65, v64
	s_waitcnt lgkmcnt(0)
	v_max3_f32 v72, v98, v64, v65
	v_sub_f32_e32 v64, v98, v72
	v_mul_f32_e32 v98, 0x3fb8aa3b, v64
	v_sub_f32_e32 v64, v99, v72
	v_mul_f32_e32 v64, 0x3fb8aa3b, v64
	v_sub_f32_e32 v68, v100, v72
	v_exp_f32_e32 v64, v64
	v_mul_f32_e32 v68, 0x3fb8aa3b, v68
	v_sub_f32_e32 v69, v102, v72
	v_exp_f32_e32 v68, v68
	v_mul_f32_e32 v69, 0x3fb8aa3b, v69
	v_sub_f32_e32 v70, v103, v72
	v_exp_f32_e32 v69, v69
	v_mul_f32_e32 v70, 0x3fb8aa3b, v70
	v_exp_f32_e32 v70, v70
	v_add_f32_e32 v65, 0, v64
	v_add_f32_e32 v65, v68, v65
	v_add_f32_e32 v65, v69, v65
	v_cvt_pk_bf16_f32 v68, v64, v68
	v_sub_f32_e32 v64, v104, v72
	v_add_f32_e32 v65, v70, v65
	v_cvt_pk_bf16_f32 v69, v69, v70
	v_mul_f32_e32 v64, 0x3fb8aa3b, v64
	v_sub_f32_e32 v70, v73, v72
	v_exp_f32_e32 v64, v64
	v_mul_f32_e32 v70, 0x3fb8aa3b, v70
	v_sub_f32_e32 v71, v74, v72
	v_exp_f32_e32 v70, v70
	v_mul_f32_e32 v71, 0x3fb8aa3b, v71
	v_sub_f32_e32 v73, v75, v72
	v_exp_f32_e32 v71, v71
	v_mul_f32_e32 v73, 0x3fb8aa3b, v73
	v_exp_f32_e32 v73, v73
	v_add_f32_e32 v65, v64, v65
	v_add_f32_e32 v65, v70, v65
	v_add_f32_e32 v65, v71, v65
	v_cvt_pk_bf16_f32 v70, v64, v70
	v_sub_f32_e32 v64, v101, v72
	v_add_f32_e32 v65, v73, v65
	v_cvt_pk_bf16_f32 v71, v71, v73
	v_mul_f32_e32 v64, 0x3fb8aa3b, v64
	v_sub_f32_e32 v73, v105, v72
	v_exp_f32_e32 v64, v64
	v_mul_f32_e32 v73, 0x3fb8aa3b, v73
	v_sub_f32_e32 v74, v106, v72
	v_exp_f32_e32 v73, v73
	v_mul_f32_e32 v74, 0x3fb8aa3b, v74
	v_sub_f32_e32 v75, v107, v72
	v_exp_f32_e32 v74, v74
	v_mul_f32_e32 v75, 0x3fb8aa3b, v75
	v_exp_f32_e32 v75, v75
	v_add_f32_e32 v65, v64, v65
	v_add_f32_e32 v65, v73, v65
	v_cvt_pk_bf16_f32 v64, v64, v73
	v_sub_f32_e32 v73, v108, v72
	v_add_f32_e32 v65, v74, v65
	v_mul_f32_e32 v73, 0x3fb8aa3b, v73
	v_add_f32_e32 v99, v75, v65
	v_cvt_pk_bf16_f32 v65, v74, v75
	v_exp_f32_e32 v74, v73
	v_sub_f32_e32 v75, v109, v72
	v_mul_f32_e32 v75, 0x3fb8aa3b, v75
	v_sub_f32_e32 v66, v66, v72
	v_exp_f32_e32 v75, v75
	v_mul_f32_e32 v66, 0x3fb8aa3b, v66
	v_sub_f32_e32 v67, v67, v72
	v_add_f32_e32 v73, v74, v99
	v_exp_f32_e32 v99, v66
	v_mul_f32_e32 v67, 0x3fb8aa3b, v67
	v_exp_f32_e32 v67, v67
	v_add_f32_e32 v73, v75, v73
	v_add_f32_e32 v66, v99, v73
	v_add_f32_e32 v73, v67, v66
	v_cvt_pk_bf16_f32 v66, v74, v75
	v_exp_f32_e32 v74, v98
	v_cvt_pk_bf16_f32 v67, v99, v67
	s_nop 0
	v_pk_mul_f32 v[98:99], v[32:33], v[74:75] op_sel_hi:[1,0]
	v_pk_mul_f32 v[32:33], v[60:61], v[74:75] op_sel_hi:[1,0]
	v_lshlrev_b32_e32 v60, 1, v81
	v_fmac_f32_e32 v73, v97, v74
	v_pk_mul_f32 v[100:101], v[34:35], v[74:75] op_sel_hi:[1,0]
	v_pk_mul_f32 v[38:39], v[38:39], v[74:75] op_sel_hi:[1,0]
	v_pk_mul_f32 v[36:37], v[36:37], v[74:75] op_sel_hi:[1,0]
	v_pk_mul_f32 v[42:43], v[42:43], v[74:75] op_sel_hi:[1,0]
	v_pk_mul_f32 v[40:41], v[40:41], v[74:75] op_sel_hi:[1,0]
	v_pk_mul_f32 v[46:47], v[46:47], v[74:75] op_sel_hi:[1,0]
	v_pk_mul_f32 v[44:45], v[44:45], v[74:75] op_sel_hi:[1,0]
	v_pk_mul_f32 v[50:51], v[50:51], v[74:75] op_sel_hi:[1,0]
	v_pk_mul_f32 v[48:49], v[48:49], v[74:75] op_sel_hi:[1,0]
	v_pk_mul_f32 v[54:55], v[54:55], v[74:75] op_sel_hi:[1,0]
	v_pk_mul_f32 v[52:53], v[52:53], v[74:75] op_sel_hi:[1,0]
	v_pk_mul_f32 v[58:59], v[58:59], v[74:75] op_sel_hi:[1,0]
	v_pk_mul_f32 v[56:57], v[56:57], v[74:75] op_sel_hi:[1,0]
	v_pk_mul_f32 v[34:35], v[62:63], v[74:75] op_sel_hi:[1,0]
	v_add3_u32 v74, s6, v96, v60
	v_add_u32_e32 v75, 0x4800, v74
	v_add_u32_e32 v97, 0x5000, v74
	s_waitcnt lgkmcnt(0)
	v_mfma_f32_16x16x32_bf16 v[60:63], v[142:145], v[68:71], v[98:101]
	s_nop 2
	v_add_u32_e32 v102, 0x5800, v74
	v_add_u32_e32 v103, 0x6000, v74
	s_waitcnt lgkmcnt(0)
	v_mfma_f32_16x16x32_bf16 v[36:39], v[146:149], v[68:71], v[36:39]
	v_add_u32_e32 v104, 0x6800, v74
	v_add_u32_e32 v105, 0x7000, v74
	s_waitcnt lgkmcnt(0)
	v_mfma_f32_16x16x32_bf16 v[40:43], v[150:153], v[68:71], v[40:43]
	v_add_u32_e32 v106, 0x7800, v74
	v_add_u32_e32 v74, 0x8800, v74
	s_waitcnt lgkmcnt(0)
	v_mfma_f32_16x16x32_bf16 v[44:47], v[154:157], v[68:71], v[44:47]
	s_waitcnt lgkmcnt(0)
	v_mfma_f32_16x16x32_bf16 v[48:51], v[158:161], v[68:71], v[48:51]
	s_waitcnt lgkmcnt(0)
	v_mfma_f32_16x16x32_bf16 v[52:55], v[162:165], v[68:71], v[52:55]
	s_waitcnt lgkmcnt(0)
	v_mfma_f32_16x16x32_bf16 v[56:59], v[166:169], v[68:71], v[56:59]
	s_waitcnt lgkmcnt(0)
	v_mfma_f32_16x16x32_bf16 v[68:71], v[170:173], v[68:71], v[32:35]
	s_nop 2
	v_mov_b32_e32 v98, v72
	s_waitcnt lgkmcnt(0)
	v_mfma_f32_16x16x32_bf16 v[32:35], v[174:177], v[64:67], v[60:63]
	s_nop 2
	v_mov_b32_e32 v97, v73
	s_waitcnt lgkmcnt(0)
	v_mfma_f32_16x16x32_bf16 v[36:39], v[178:181], v[64:67], v[36:39]
	s_waitcnt lgkmcnt(0)
	v_mfma_f32_16x16x32_bf16 v[40:43], v[182:185], v[64:67], v[40:43]
	s_waitcnt lgkmcnt(0)
	v_mfma_f32_16x16x32_bf16 v[44:47], v[186:189], v[64:67], v[44:47]
	s_waitcnt lgkmcnt(0)
	v_mfma_f32_16x16x32_bf16 v[48:51], v[190:193], v[64:67], v[48:51]
	s_waitcnt lgkmcnt(0)
	v_mfma_f32_16x16x32_bf16 v[52:55], v[194:197], v[64:67], v[52:55]
	s_waitcnt lgkmcnt(0)
	v_mfma_f32_16x16x32_bf16 v[56:59], v[198:201], v[64:67], v[56:59]
	s_waitcnt lgkmcnt(0)
	v_mfma_f32_16x16x32_bf16 v[60:63], v[202:205], v[64:67], v[68:71]
	s_branch .LBB0_816
